# GEMM tile prologue: first LDS-DMA loads issued before the accumulator zeroing (zeroing overlaps the first memory round trip) at all three LDS-DMA GEMM sites
# speedup vs baseline: 1.0860x; 1.0019x over previous
; DI char* opq(char* q) { size_t z = 0; asm volatile("" : "+s"(z)); return q + z; }
; DI int tidx() { int t = threadIdx.x; asm volatile("" : "+v"(t)); return t; }
; #define GLOAD(dst, kt_) _Pragma("unroll") for (int i = 0; i < NCH; ++i) { dst[i] = (i < NCHW) ? ldw(i, tid >> 3, (kt_) * 64 + (tid & 7) * 8) : ldx(i - NCHW, tid >> 3, (kt_) * 64 + (tid & 7) * 8); }
; #define LSTORE(src, base) _Pragma("unroll") for (int i = 0; i < NCH; ++i) { const int c = tid + 256 * i; *(u32x4*)((base) + (c >> 3) * 144 + (c & 7) * 16) = src[i]; }
; template <int WGN, int INS, int IMS, bool DB, class LdW, class LdX>
; DI void gemm_core(f32x16 (&acc)[INS][IMS], const int KT, LdW ldw, LdX ldx, char* lds, const int tid) {
;   constexpr int WGM = 4 / WGN;
;   constexpr int WROWS = WGN * 32 * INS, XROWS = WGM * 32 * IMS, NROWS = WROWS + XROWS, NCH = NROWS / 32, NCHW = WROWS / 32, BUFB = NROWS * 144;
;   const int lane = tid & 63, wid = tid >> 6, l31 = lane & 31, hi = lane >> 5;
;   const int wn = (WGN == 2) ? (wid >> 1) : wid, wm = (WGN == 2) ? (wid & 1) : 0;
;   const int offa = (wn * 32 * INS + l31) * 144 + hi * 16;
;   const int offb = (WROWS + wm * 32 * IMS + l31) * 144 + hi * 16;
; #pragma unroll
;   for (int a = 0; a < INS; ++a)
; #pragma unroll
;     for (int b = 0; b < IMS; ++b)
; #pragma unroll
;       for (int r = 0; r < 16; ++r) acc[a][b][r] = 0.f;
;     ...
;   if (DB) {
;     u32x4 preA[NCH], preB[NCH];
;     GLOAD(preA, 0)
;     GLOAD(preB, 1)
;     __syncthreads();
;     LSTORE(preA, lds)
;     __syncthreads();
; template <int NTW>
; DI void inproj_tile(const Params& p, int l, int mt, int ntile, char* lds) {
;   char* const ws_ = opq(p.ws);
;   const u16* W = (const u16*)(ws_ + OFF_WIN) + ((size_t)l * NP + ntile * 64 * NTW) * 1024;
;   const u16* X = (const u16*)(ws_ + OFF_XB) + (size_t)mt * 128 * 1024;
;   f32x16 acc[NTW][2];
;   const int tid = tidx();
;   gemm_core<2, NTW, 2, (NTW == 2)>(acc, 16, [&](int i, int r0, int k) -> u32x4 { return *(const u32x4*)((W + i * 32768) + (unsigned)(r0 * 1024 + k)); },
;                [&](int i, int r0, int k) -> u32x4 { return *(const u32x4*)((X + i * 32768) + (unsigned)(r0 * 1024 + k)); }, lds, tid);
.LBB0_163:
	s_lshl_b32 s0, s26, 4
	s_and_b32 s0, s0, 0x70
	s_bfe_u32 s1, s26, 0x40003
	s_or_b32 s4, s0, s1
	s_mov_b64 s[0:1], 0
	s_add_u32 s27, s90, s0
	s_addc_u32 s28, s91, s1
	s_lshl_b32 s0, s26, 1
	s_and_b32 s0, s0, 0xffffff00
	v_readlane_b32 s2, v234, 24
	s_ashr_i32 s1, s0, 31
	s_mulk_i32 s2, 0xd00
	s_add_u32 s2, s0, s2
	s_addc_u32 s3, s1, 0
	s_lshl_b64 s[2:3], s[2:3], 11
	s_add_u32 s2, s27, s2
	s_addc_u32 s3, s28, s3
	s_lshl_b32 s80, s4, 7
	s_lshl_b32 s4, s4, 18
	s_add_u32 s24, s27, s4
	s_addc_u32 s25, s28, 0
	s_add_u32 s4, s24, 0x2a40000
	s_addc_u32 s5, s25, 0
	v_mov_b32_e32 v181, v176
	v_and_b32_e32 v183, 0x5f, v181
	v_lshrrev_b32_e32 v185, 3, v181
	v_or_b32_e32 v254, s80, v183
	v_lshlrev_b32_e32 v254, 2, v254
	s_add_u32 s14, s27, 0x4a40000
	s_addc_u32 s15, s28, 0
	global_load_dword v252, v254, s[14:15] sc1
	global_load_dword v253, v254, s[14:15] offset:128 sc1
	v_and_b32_e32 v220, 63, v181
	v_lshrrev_b32_e32 v221, 6, v181
	v_lshrrev_b32_e32 v222, 3, v220
	v_readfirstlane_b32 s13, v221
	v_and_b32_e32 v223, 7, v220
	v_bfe_u32 v224, v220, 4, 2
	v_xor_b32_e32 v223, v223, v224
	v_lshlrev_b32_e32 v223, 4, v223
	v_and_b32_e32 v224, 1, v221
	v_lshrrev_b32_e32 v225, 1, v221
	v_lshlrev_b32_e32 v224, 5, v224
	v_lshl_add_u32 v224, v225, 7, v224
	v_add_u32_e32 v224, v224, v222
	v_lshl_add_u32 v225, v221, 5, v222
	v_lshl_or_b32 v210, v224, 11, v223
	v_lshl_or_b32 v216, v225, 11, v223
	v_xor_b32_e32 v224, 64, v210
	v_xor_b32_e32 v225, 64, v216
	v_add_u32_e32 v211, 0x3c00, v224
	v_add_u32_e32 v217, 0x3c00, v225
	v_add_u32_e32 v212, 0x7800, v210
	v_add_u32_e32 v218, 0x7800, v216
	v_add_u32_e32 v213, 0xb400, v224
	v_add_u32_e32 v219, 0xb400, v225
	v_and_b32_e32 v222, 31, v220
	v_lshrrev_b32_e32 v223, 5, v220
	v_bfe_u32 v224, v220, 1, 3
	v_xor_b32_e32 v223, v223, v224
	v_lshlrev_b32_e32 v223, 4, v223
	v_lshrrev_b32_e32 v224, 1, v221
	v_and_b32_e32 v225, 1, v221
	v_lshl_add_u32 v224, v224, 6, v222
	v_lshl_add_u32 v225, v225, 6, v222
	v_lshl_or_b32 v202, v224, 7, v223
	v_lshl_or_b32 v206, v225, 7, v223
	v_xor_b32_e32 v203, 32, v202
	v_xor_b32_e32 v207, 32, v206
	v_xor_b32_e32 v204, 64, v202
	v_xor_b32_e32 v208, 64, v206
	v_xor_b32_e32 v205, 96, v202
	v_xor_b32_e32 v209, 96, v206
	s_lshl_b32 s13, s13, 12
	s_sub_u32 s10, s4, 0x80
	s_subb_u32 s11, s5, 0
	s_add_u32 s8, s2, 0x1ff80
	s_addc_u32 s9, s3, 0
	s_sub_u32 s6, s2, 0x80
	s_subb_u32 s7, s3, 0
	s_mov_b32 s12, 0
	s_waitcnt lgkmcnt(0)
	s_barrier
	s_add_u32 s10, s10, 0x80
	s_addc_u32 s11, s11, 0
	s_add_u32 m0, s13, 0
	s_nop 0
	global_load_lds_dwordx4 v216, s[10:11] sc1
	global_load_lds_dwordx4 v217, s[10:11] offset:1024 sc1
	global_load_lds_dwordx4 v218, s[10:11] offset:2048 sc1
	global_load_lds_dwordx4 v219, s[10:11] offset:3072 sc1
	s_add_u32 s6, s6, 0x80
	s_addc_u32 s7, s7, 0
	s_add_u32 m0, s13, 32768
	s_nop 0
	global_load_lds_dwordx4 v210, s[6:7]
	global_load_lds_dwordx4 v211, s[6:7] offset:1024
	global_load_lds_dwordx4 v212, s[6:7] offset:2048
	global_load_lds_dwordx4 v213, s[6:7] offset:3072
	v_mov_b32_e32 v112, 0
	v_mov_b32_e32 v113, 0
	v_mov_b32_e32 v114, 0
	v_mov_b32_e32 v115, 0
	v_mov_b32_e32 v116, 0
	v_mov_b32_e32 v117, 0
	v_mov_b32_e32 v118, 0
	v_mov_b32_e32 v119, 0
	v_mov_b32_e32 v120, 0
	v_mov_b32_e32 v121, 0
	v_mov_b32_e32 v122, 0
	v_mov_b32_e32 v123, 0
	v_mov_b32_e32 v124, 0
	v_mov_b32_e32 v125, 0
	v_mov_b32_e32 v126, 0
	v_mov_b32_e32 v127, 0
	v_mov_b32_e32 v48, 0
	v_mov_b32_e32 v49, 0
	v_mov_b32_e32 v50, 0
	v_mov_b32_e32 v51, 0
	v_mov_b32_e32 v52, 0
	v_mov_b32_e32 v53, 0
	v_mov_b32_e32 v54, 0
	v_mov_b32_e32 v55, 0
	v_mov_b32_e32 v56, 0
	v_mov_b32_e32 v57, 0
	v_mov_b32_e32 v58, 0
	v_mov_b32_e32 v59, 0
	v_mov_b32_e32 v60, 0
	v_mov_b32_e32 v61, 0
	v_mov_b32_e32 v62, 0
	v_mov_b32_e32 v63, 0
	v_mov_b32_e32 v96, 0
	v_mov_b32_e32 v97, 0
	v_mov_b32_e32 v98, 0
	v_mov_b32_e32 v99, 0
	v_mov_b32_e32 v100, 0
	v_mov_b32_e32 v101, 0
	v_mov_b32_e32 v102, 0
	v_mov_b32_e32 v103, 0
	v_mov_b32_e32 v104, 0
	v_mov_b32_e32 v105, 0
	v_mov_b32_e32 v106, 0
	v_mov_b32_e32 v107, 0
	v_mov_b32_e32 v108, 0
	v_mov_b32_e32 v109, 0
	v_mov_b32_e32 v110, 0
	v_mov_b32_e32 v111, 0
	v_mov_b32_e32 v32, 0
	v_mov_b32_e32 v33, 0
	v_mov_b32_e32 v34, 0
	v_mov_b32_e32 v35, 0
	v_mov_b32_e32 v36, 0
	v_mov_b32_e32 v37, 0
	v_mov_b32_e32 v38, 0
	v_mov_b32_e32 v39, 0
	v_mov_b32_e32 v40, 0
	v_mov_b32_e32 v41, 0
	v_mov_b32_e32 v42, 0
	v_mov_b32_e32 v43, 0
	v_mov_b32_e32 v44, 0
	v_mov_b32_e32 v45, 0
	v_mov_b32_e32 v46, 0
	v_mov_b32_e32 v47, 0
	v_mov_b32_e32 v80, 0
	v_mov_b32_e32 v81, 0
	v_mov_b32_e32 v82, 0
	v_mov_b32_e32 v83, 0
	v_mov_b32_e32 v84, 0
	v_mov_b32_e32 v85, 0
	v_mov_b32_e32 v86, 0
	v_mov_b32_e32 v87, 0
	v_mov_b32_e32 v88, 0
	v_mov_b32_e32 v89, 0
	v_mov_b32_e32 v90, 0
	v_mov_b32_e32 v91, 0
	v_mov_b32_e32 v92, 0
	v_mov_b32_e32 v93, 0
	v_mov_b32_e32 v94, 0
	v_mov_b32_e32 v95, 0
	v_mov_b32_e32 v16, 0
	v_mov_b32_e32 v17, 0
	v_mov_b32_e32 v18, 0
	v_mov_b32_e32 v19, 0
	v_mov_b32_e32 v20, 0
	v_mov_b32_e32 v21, 0
	v_mov_b32_e32 v22, 0
	v_mov_b32_e32 v23, 0
	v_mov_b32_e32 v24, 0
	v_mov_b32_e32 v25, 0
	v_mov_b32_e32 v26, 0
	v_mov_b32_e32 v27, 0
	v_mov_b32_e32 v28, 0
	v_mov_b32_e32 v29, 0
	v_mov_b32_e32 v30, 0
	v_mov_b32_e32 v31, 0
	v_mov_b32_e32 v64, 0
	v_mov_b32_e32 v65, 0
	v_mov_b32_e32 v66, 0
	v_mov_b32_e32 v67, 0
	v_mov_b32_e32 v68, 0
	v_mov_b32_e32 v69, 0
	v_mov_b32_e32 v70, 0
	v_mov_b32_e32 v71, 0
	v_mov_b32_e32 v72, 0
	v_mov_b32_e32 v73, 0
	v_mov_b32_e32 v74, 0
	v_mov_b32_e32 v75, 0
	v_mov_b32_e32 v76, 0
	v_mov_b32_e32 v77, 0
	v_mov_b32_e32 v78, 0
	v_mov_b32_e32 v79, 0
	v_mov_b32_e32 v0, 0
	v_mov_b32_e32 v1, 0
	v_mov_b32_e32 v2, 0
	v_mov_b32_e32 v3, 0
	v_mov_b32_e32 v4, 0
	v_mov_b32_e32 v5, 0
	v_mov_b32_e32 v6, 0
	v_mov_b32_e32 v7, 0
	v_mov_b32_e32 v8, 0
	v_mov_b32_e32 v9, 0
	v_mov_b32_e32 v10, 0
	v_mov_b32_e32 v11, 0
	v_mov_b32_e32 v12, 0
	v_mov_b32_e32 v13, 0
	v_mov_b32_e32 v14, 0
	v_mov_b32_e32 v15, 0

; DI char* opq(char* q) { size_t z = 0; asm volatile("" : "+s"(z)); return q + z; }
; DI int tidx() { int t = threadIdx.x; asm volatile("" : "+v"(t)); return t; }
; template <int NTW>
; DI void inproj_tile(const Params& p, int l, int mt, int ntile, char* lds) {
;   char* const ws_ = opq(p.ws);
;   const u16* W = (const u16*)(ws_ + OFF_WIN) + ((size_t)l * NP + ntile * 64 * NTW) * 1024;
;   const u16* X = (const u16*)(ws_ + OFF_XB) + (size_t)mt * 128 * 1024;
;   f32x16 acc[NTW][2];
;   const int tid = tidx();
;   gemm_core<2, NTW, 2, (NTW == 2)>(acc, 16, [&](int i, int r0, int k) -> u32x4 { return *(const u32x4*)((W + i * 32768) + (unsigned)(r0 * 1024 + k)); },
;                [&](int i, int r0, int k) -> u32x4 { return *(const u32x4*)((X + i * 32768) + (unsigned)(r0 * 1024 + k)); }, lds, tid);
; __global__ void __launch_bounds__(256, 2) hybrid_megakernel(Params p) {
;     ...
;       { const int q2 = vb >> 3; inproj_tile<4>(p, l, (vb & 7) * 16 + (q2 & 15), 8 + (q2 >> 4), lds); }
.Lb_tile:
	s_lshl_b32 s0, s36, 4
	s_and_b32 s0, s0, 0x70
	s_bfe_u32 s1, s36, 0x40003
	s_or_b32 s4, s0, s1
	s_mov_b64 s[0:1], 0
	s_add_u32 s27, s90, s0
	s_addc_u32 s37, s91, s1
	s_lshl_b32 s0, s36, 1
	s_and_b32 s0, s0, 0xffffff00
	s_addk_i32 s0, 0x800
	s_ashr_i32 s1, s0, 31
	s_add_u32 s2, s0, s28
	s_addc_u32 s3, s1, 0
	s_lshl_b64 s[2:3], s[2:3], 11
	s_add_u32 s2, s27, s2
	s_addc_u32 s3, s37, s3
	s_lshl_b32 s80, s4, 7
	s_lshl_b32 s26, s4, 18
	s_add_u32 s24, s27, s26
	s_addc_u32 s25, s37, 0
	s_add_u32 s4, s24, 0x2a40000
	s_addc_u32 s5, s25, 0
	v_mov_b32_e32 v181, v176
	v_and_b32_e32 v183, 0x5f, v181
	v_lshrrev_b32_e32 v185, 3, v181
	v_or_b32_e32 v254, s80, v183
	v_lshlrev_b32_e32 v254, 2, v254
	s_add_u32 s14, s27, 0x4a40000
	s_addc_u32 s15, s37, 0
	global_load_dword v252, v254, s[14:15] sc1
	global_load_dword v253, v254, s[14:15] offset:128 sc1
	v_and_b32_e32 v220, 63, v181
	v_lshrrev_b32_e32 v221, 6, v181
	v_lshrrev_b32_e32 v222, 3, v220
	v_readfirstlane_b32 s13, v221
	v_and_b32_e32 v223, 7, v220
	v_bfe_u32 v224, v220, 4, 2
	v_xor_b32_e32 v223, v223, v224
	v_lshlrev_b32_e32 v223, 4, v223
	v_and_b32_e32 v224, 1, v221
	v_lshrrev_b32_e32 v225, 1, v221
	v_lshlrev_b32_e32 v224, 5, v224
	v_lshl_add_u32 v224, v225, 7, v224
	v_add_u32_e32 v224, v224, v222
	v_lshl_add_u32 v225, v221, 5, v222
	v_lshl_or_b32 v210, v224, 11, v223
	v_lshl_or_b32 v216, v225, 11, v223
	v_xor_b32_e32 v224, 64, v210
	v_xor_b32_e32 v225, 64, v216
	v_add_u32_e32 v211, 0x3c00, v224
	v_add_u32_e32 v217, 0x3c00, v225
	v_add_u32_e32 v212, 0x7800, v210
	v_add_u32_e32 v218, 0x7800, v216
	v_add_u32_e32 v213, 0xb400, v224
	v_add_u32_e32 v219, 0xb400, v225
	v_and_b32_e32 v222, 31, v220
	v_lshrrev_b32_e32 v223, 5, v220
	v_bfe_u32 v224, v220, 1, 3
	v_xor_b32_e32 v223, v223, v224
	v_lshlrev_b32_e32 v223, 4, v223
	v_lshrrev_b32_e32 v224, 1, v221
	v_and_b32_e32 v225, 1, v221
	v_lshl_add_u32 v224, v224, 6, v222
	v_lshl_add_u32 v225, v225, 6, v222
	v_lshl_or_b32 v202, v224, 7, v223
	v_lshl_or_b32 v206, v225, 7, v223
	v_xor_b32_e32 v203, 32, v202
	v_xor_b32_e32 v207, 32, v206
	v_xor_b32_e32 v204, 64, v202
	v_xor_b32_e32 v208, 64, v206
	v_xor_b32_e32 v205, 96, v202
	v_xor_b32_e32 v209, 96, v206
	s_lshl_b32 s13, s13, 12
	s_sub_u32 s10, s4, 0x80
	s_subb_u32 s11, s5, 0
	s_add_u32 s8, s2, 0x1ff80
	s_addc_u32 s9, s3, 0
	s_sub_u32 s6, s2, 0x80
	s_subb_u32 s7, s3, 0
	s_mov_b32 s12, 0
	s_setprio 2
	s_waitcnt lgkmcnt(0)
	s_barrier
	s_add_u32 s10, s10, 0x80
	s_addc_u32 s11, s11, 0
	s_add_u32 m0, s13, 0
	s_nop 0
	global_load_lds_dwordx4 v216, s[10:11] sc1
	global_load_lds_dwordx4 v217, s[10:11] offset:1024 sc1
	global_load_lds_dwordx4 v218, s[10:11] offset:2048 sc1
	global_load_lds_dwordx4 v219, s[10:11] offset:3072 sc1
	s_add_u32 s6, s6, 0x80
	s_addc_u32 s7, s7, 0
	s_add_u32 m0, s13, 32768
	s_nop 0
	global_load_lds_dwordx4 v210, s[6:7]
	global_load_lds_dwordx4 v211, s[6:7] offset:1024
	global_load_lds_dwordx4 v212, s[6:7] offset:2048
	global_load_lds_dwordx4 v213, s[6:7] offset:3072
	v_mov_b32_e32 v112, 0
	v_mov_b32_e32 v113, 0
	v_mov_b32_e32 v114, 0
	v_mov_b32_e32 v115, 0
	v_mov_b32_e32 v116, 0
	v_mov_b32_e32 v117, 0
	v_mov_b32_e32 v118, 0
	v_mov_b32_e32 v119, 0
	v_mov_b32_e32 v120, 0
	v_mov_b32_e32 v121, 0
	v_mov_b32_e32 v122, 0
	v_mov_b32_e32 v123, 0
	v_mov_b32_e32 v124, 0
	v_mov_b32_e32 v125, 0
	v_mov_b32_e32 v126, 0
	v_mov_b32_e32 v127, 0
	v_mov_b32_e32 v48, 0
	v_mov_b32_e32 v49, 0
	v_mov_b32_e32 v50, 0
	v_mov_b32_e32 v51, 0
	v_mov_b32_e32 v52, 0
	v_mov_b32_e32 v53, 0
	v_mov_b32_e32 v54, 0
	v_mov_b32_e32 v55, 0
	v_mov_b32_e32 v56, 0
	v_mov_b32_e32 v57, 0
	v_mov_b32_e32 v58, 0
	v_mov_b32_e32 v59, 0
	v_mov_b32_e32 v60, 0
	v_mov_b32_e32 v61, 0
	v_mov_b32_e32 v62, 0
	v_mov_b32_e32 v63, 0
	v_mov_b32_e32 v96, 0
	v_mov_b32_e32 v97, 0
	v_mov_b32_e32 v98, 0
	v_mov_b32_e32 v99, 0
	v_mov_b32_e32 v100, 0
	v_mov_b32_e32 v101, 0
	v_mov_b32_e32 v102, 0
	v_mov_b32_e32 v103, 0
	v_mov_b32_e32 v104, 0
	v_mov_b32_e32 v105, 0
	v_mov_b32_e32 v106, 0
	v_mov_b32_e32 v107, 0
	v_mov_b32_e32 v108, 0
	v_mov_b32_e32 v109, 0
	v_mov_b32_e32 v110, 0
	v_mov_b32_e32 v111, 0
	v_mov_b32_e32 v32, 0
	v_mov_b32_e32 v33, 0
	v_mov_b32_e32 v34, 0
	v_mov_b32_e32 v35, 0
	v_mov_b32_e32 v36, 0
	v_mov_b32_e32 v37, 0
	v_mov_b32_e32 v38, 0
	v_mov_b32_e32 v39, 0
	v_mov_b32_e32 v40, 0
	v_mov_b32_e32 v41, 0
	v_mov_b32_e32 v42, 0
	v_mov_b32_e32 v43, 0
	v_mov_b32_e32 v44, 0
	v_mov_b32_e32 v45, 0
	v_mov_b32_e32 v46, 0
	v_mov_b32_e32 v47, 0
	v_mov_b32_e32 v80, 0
	v_mov_b32_e32 v81, 0
	v_mov_b32_e32 v82, 0
	v_mov_b32_e32 v83, 0
	v_mov_b32_e32 v84, 0
	v_mov_b32_e32 v85, 0
	v_mov_b32_e32 v86, 0
	v_mov_b32_e32 v87, 0
	v_mov_b32_e32 v88, 0
	v_mov_b32_e32 v89, 0
	v_mov_b32_e32 v90, 0
	v_mov_b32_e32 v91, 0
	v_mov_b32_e32 v92, 0
	v_mov_b32_e32 v93, 0
	v_mov_b32_e32 v94, 0
	v_mov_b32_e32 v95, 0
	v_mov_b32_e32 v16, 0
	v_mov_b32_e32 v17, 0
	v_mov_b32_e32 v18, 0
	v_mov_b32_e32 v19, 0
	v_mov_b32_e32 v20, 0
	v_mov_b32_e32 v21, 0
	v_mov_b32_e32 v22, 0
	v_mov_b32_e32 v23, 0
	v_mov_b32_e32 v24, 0
	v_mov_b32_e32 v25, 0
	v_mov_b32_e32 v26, 0
	v_mov_b32_e32 v27, 0
	v_mov_b32_e32 v28, 0
	v_mov_b32_e32 v29, 0
	v_mov_b32_e32 v30, 0
	v_mov_b32_e32 v31, 0
	v_mov_b32_e32 v64, 0
	v_mov_b32_e32 v65, 0
	v_mov_b32_e32 v66, 0
	v_mov_b32_e32 v67, 0
	v_mov_b32_e32 v68, 0
	v_mov_b32_e32 v69, 0
	v_mov_b32_e32 v70, 0
	v_mov_b32_e32 v71, 0
	v_mov_b32_e32 v72, 0
	v_mov_b32_e32 v73, 0
	v_mov_b32_e32 v74, 0
	v_mov_b32_e32 v75, 0
	v_mov_b32_e32 v76, 0
	v_mov_b32_e32 v77, 0
	v_mov_b32_e32 v78, 0
	v_mov_b32_e32 v79, 0
	v_mov_b32_e32 v0, 0
	v_mov_b32_e32 v1, 0
	v_mov_b32_e32 v2, 0
	v_mov_b32_e32 v3, 0
	v_mov_b32_e32 v4, 0
	v_mov_b32_e32 v5, 0
	v_mov_b32_e32 v6, 0
	v_mov_b32_e32 v7, 0
	v_mov_b32_e32 v8, 0
	v_mov_b32_e32 v9, 0
	v_mov_b32_e32 v10, 0
	v_mov_b32_e32 v11, 0
	v_mov_b32_e32 v12, 0
	v_mov_b32_e32 v13, 0
	v_mov_b32_e32 v14, 0
	v_mov_b32_e32 v15, 0

; DI char* opq(char* q) { size_t z = 0; asm volatile("" : "+s"(z)); return q + z; }
; DI int tidx() { int t = threadIdx.x; asm volatile("" : "+v"(t)); return t; }
; #define GLOAD(dst, kt_) _Pragma("unroll") for (int i = 0; i < NCH; ++i) { dst[i] = (i < NCHW) ? ldw(i, tid >> 3, (kt_) * 64 + (tid & 7) * 8) : ldx(i - NCHW, tid >> 3, (kt_) * 64 + (tid & 7) * 8); }
; #define LSTORE(src, base) _Pragma("unroll") for (int i = 0; i < NCH; ++i) { const int c = tid + 256 * i; *(u32x4*)((base) + (c >> 3) * 144 + (c & 7) * 16) = src[i]; }
; template <int WGN, int INS, int IMS, bool DB, class LdW, class LdX>
; DI void gemm_core(f32x16 (&acc)[INS][IMS], const int KT, LdW ldw, LdX ldx, char* lds, const int tid) {
;   constexpr int WGM = 4 / WGN;
;   constexpr int WROWS = WGN * 32 * INS, XROWS = WGM * 32 * IMS, NROWS = WROWS + XROWS, NCH = NROWS / 32, NCHW = WROWS / 32, BUFB = NROWS * 144;
;   const int lane = tid & 63, wid = tid >> 6, l31 = lane & 31, hi = lane >> 5;
;   const int wn = (WGN == 2) ? (wid >> 1) : wid, wm = (WGN == 2) ? (wid & 1) : 0;
;   const int offa = (wn * 32 * INS + l31) * 144 + hi * 16;
;   const int offb = (WROWS + wm * 32 * IMS + l31) * 144 + hi * 16;
; #pragma unroll
;   for (int a = 0; a < INS; ++a)
; #pragma unroll
;     for (int b = 0; b < IMS; ++b)
; #pragma unroll
;       for (int r = 0; r < 16; ++r) acc[a][b][r] = 0.f;
;     ...
;   if (DB) {
;     u32x4 preA[NCH], preB[NCH];
;     GLOAD(preA, 0)
;     GLOAD(preB, 1)
;     __syncthreads();
;     LSTORE(preA, lds)
;     __syncthreads();
; DI void outproj_item(const Params& p, int l, int it, char* lds) {
;   char* const ws_ = opq(p.ws);
;   const int mt = (it & 7) * 16 + ((it >> 3) & 15), nt = it >> 7;
;   const u16* W = (const u16*)(ws_ + OFF_WOUT) + ((size_t)l * 1024 + nt * 256) * 1024;
;   const u16* Y = (const u16*)(ws_ + OFF_XB) + (size_t)mt * 128 * 1024;
;   f32x16 acc[4][2];
;   const int tid = tidx();
;   gemm_core<2, 4, 2, false>(acc, 16, [&](int i, int r0, int k) -> u32x4 { return *(const u32x4*)((W + i * 32768) + (unsigned)(r0 * 1024 + k)); },
;                [&](int i, int r0, int k) -> u32x4 { return *(const u32x4*)((Y + i * 32768) + (unsigned)(r0 * 1024 + k)); }, lds, tid);
.LBB0_533:
	s_mov_b64 s[0:1], 0
	s_add_u32 s28, s90, s0
	s_addc_u32 s29, s91, s1
	s_lshl_b32 s0, s27, 4
	s_and_b32 s0, s0, 0x70
	s_bfe_u32 s1, s27, 0x40003
	s_ashr_i32 s30, s27, 7
	s_or_b32 s4, s0, s1
	s_lshl_b32 s0, s30, 8
	s_ashr_i32 s1, s0, 31
	s_add_u32 s5, s28, s26
	s_addc_u32 s6, s29, 0
	s_lshl_b64 s[2:3], s[0:1], 11
	s_add_u32 s18, s5, s2
	s_addc_u32 s19, s6, s3
	s_add_u32 s2, s18, 0x1a00000
	s_addc_u32 s3, s19, 0
	s_lshl_b32 s80, s4, 7
	s_lshl_b32 s4, s4, 18
	s_add_u32 s24, s28, s4
	s_addc_u32 s25, s29, 0
	s_add_u32 s4, s24, 0x2a40000
	s_addc_u32 s5, s25, 0
	v_mov_b32_e32 v181, v176
	v_and_b32_e32 v183, 0x5f, v181
	v_lshlrev_b32_e32 v185, 4, v181
	v_and_b32_e32 v220, 63, v181
	v_lshrrev_b32_e32 v221, 6, v181
	v_lshrrev_b32_e32 v222, 3, v220
	v_readfirstlane_b32 s13, v221
	v_and_b32_e32 v223, 7, v220
	v_bfe_u32 v224, v220, 4, 2
	v_xor_b32_e32 v223, v223, v224
	v_lshlrev_b32_e32 v223, 4, v223
	v_and_b32_e32 v224, 1, v221
	v_lshrrev_b32_e32 v225, 1, v221
	v_lshlrev_b32_e32 v224, 5, v224
	v_lshl_add_u32 v224, v225, 7, v224
	v_add_u32_e32 v224, v224, v222
	v_lshl_add_u32 v225, v221, 5, v222
	v_lshl_or_b32 v210, v224, 11, v223
	v_lshl_or_b32 v216, v225, 11, v223
	v_xor_b32_e32 v224, 64, v210
	v_xor_b32_e32 v225, 64, v216
	v_add_u32_e32 v211, 0x3c00, v224
	v_add_u32_e32 v217, 0x3c00, v225
	v_add_u32_e32 v212, 0x7800, v210
	v_add_u32_e32 v218, 0x7800, v216
	v_add_u32_e32 v213, 0xb400, v224
	v_add_u32_e32 v219, 0xb400, v225
	v_and_b32_e32 v222, 31, v220
	v_lshrrev_b32_e32 v223, 5, v220
	v_bfe_u32 v224, v220, 1, 3
	v_xor_b32_e32 v223, v223, v224
	v_lshlrev_b32_e32 v223, 4, v223
	v_lshrrev_b32_e32 v224, 1, v221
	v_and_b32_e32 v225, 1, v221
	v_lshl_add_u32 v224, v224, 6, v222
	v_lshl_add_u32 v225, v225, 6, v222
	v_lshl_or_b32 v202, v224, 7, v223
	v_lshl_or_b32 v206, v225, 7, v223
	v_xor_b32_e32 v203, 32, v202
	v_xor_b32_e32 v207, 32, v206
	v_xor_b32_e32 v204, 64, v202
	v_xor_b32_e32 v208, 64, v206
	v_xor_b32_e32 v205, 96, v202
	v_xor_b32_e32 v209, 96, v206
	s_lshl_b32 s13, s13, 12
	s_sub_u32 s10, s4, 0x80
	s_subb_u32 s11, s5, 0
	s_add_u32 s8, s2, 0x1ff80
	s_addc_u32 s9, s3, 0
	s_sub_u32 s6, s2, 0x80
	s_subb_u32 s7, s3, 0
	s_mov_b32 s12, 0
	s_waitcnt lgkmcnt(0)
	s_barrier
	s_add_u32 s10, s10, 0x80
	s_addc_u32 s11, s11, 0
	s_add_u32 m0, s13, 0
	s_nop 0
	global_load_lds_dwordx4 v216, s[10:11] sc1
	global_load_lds_dwordx4 v217, s[10:11] offset:1024 sc1
	global_load_lds_dwordx4 v218, s[10:11] offset:2048 sc1
	global_load_lds_dwordx4 v219, s[10:11] offset:3072 sc1
	s_add_u32 s6, s6, 0x80
	s_addc_u32 s7, s7, 0
	s_add_u32 m0, s13, 32768
	s_nop 0
	global_load_lds_dwordx4 v210, s[6:7]
	global_load_lds_dwordx4 v211, s[6:7] offset:1024
	global_load_lds_dwordx4 v212, s[6:7] offset:2048
	global_load_lds_dwordx4 v213, s[6:7] offset:3072
	v_mov_b32_e32 v112, 0
	v_mov_b32_e32 v113, 0
	v_mov_b32_e32 v114, 0
	v_mov_b32_e32 v115, 0
	v_mov_b32_e32 v116, 0
	v_mov_b32_e32 v117, 0
	v_mov_b32_e32 v118, 0
	v_mov_b32_e32 v119, 0
	v_mov_b32_e32 v120, 0
	v_mov_b32_e32 v121, 0
	v_mov_b32_e32 v122, 0
	v_mov_b32_e32 v123, 0
	v_mov_b32_e32 v124, 0
	v_mov_b32_e32 v125, 0
	v_mov_b32_e32 v126, 0
	v_mov_b32_e32 v127, 0
	v_mov_b32_e32 v64, 0
	v_mov_b32_e32 v65, 0
	v_mov_b32_e32 v66, 0
	v_mov_b32_e32 v67, 0
	v_mov_b32_e32 v68, 0
	v_mov_b32_e32 v69, 0
	v_mov_b32_e32 v70, 0
	v_mov_b32_e32 v71, 0
	v_mov_b32_e32 v72, 0
	v_mov_b32_e32 v73, 0
	v_mov_b32_e32 v74, 0
	v_mov_b32_e32 v75, 0
	v_mov_b32_e32 v76, 0
	v_mov_b32_e32 v77, 0
	v_mov_b32_e32 v78, 0
	v_mov_b32_e32 v79, 0
	v_mov_b32_e32 v96, 0
	v_mov_b32_e32 v97, 0
	v_mov_b32_e32 v98, 0
	v_mov_b32_e32 v99, 0
	v_mov_b32_e32 v100, 0
	v_mov_b32_e32 v101, 0
	v_mov_b32_e32 v102, 0
	v_mov_b32_e32 v103, 0
	v_mov_b32_e32 v104, 0
	v_mov_b32_e32 v105, 0
	v_mov_b32_e32 v106, 0
	v_mov_b32_e32 v107, 0
	v_mov_b32_e32 v108, 0
	v_mov_b32_e32 v109, 0
	v_mov_b32_e32 v110, 0
	v_mov_b32_e32 v111, 0
	v_mov_b32_e32 v32, 0
	v_mov_b32_e32 v33, 0
	v_mov_b32_e32 v34, 0
	v_mov_b32_e32 v35, 0
	v_mov_b32_e32 v36, 0
	v_mov_b32_e32 v37, 0
	v_mov_b32_e32 v38, 0
	v_mov_b32_e32 v39, 0
	v_mov_b32_e32 v40, 0
	v_mov_b32_e32 v41, 0
	v_mov_b32_e32 v42, 0
	v_mov_b32_e32 v43, 0
	v_mov_b32_e32 v44, 0
	v_mov_b32_e32 v45, 0
	v_mov_b32_e32 v46, 0
	v_mov_b32_e32 v47, 0
	v_mov_b32_e32 v80, 0
	v_mov_b32_e32 v81, 0
	v_mov_b32_e32 v82, 0
	v_mov_b32_e32 v83, 0
	v_mov_b32_e32 v84, 0
	v_mov_b32_e32 v85, 0
	v_mov_b32_e32 v86, 0
	v_mov_b32_e32 v87, 0
	v_mov_b32_e32 v88, 0
	v_mov_b32_e32 v89, 0
	v_mov_b32_e32 v90, 0
	v_mov_b32_e32 v91, 0
	v_mov_b32_e32 v92, 0
	v_mov_b32_e32 v93, 0
	v_mov_b32_e32 v94, 0
	v_mov_b32_e32 v95, 0
	v_mov_b32_e32 v16, 0
	v_mov_b32_e32 v17, 0
	v_mov_b32_e32 v18, 0
	v_mov_b32_e32 v19, 0
	v_mov_b32_e32 v20, 0
	v_mov_b32_e32 v21, 0
	v_mov_b32_e32 v22, 0
	v_mov_b32_e32 v23, 0
	v_mov_b32_e32 v24, 0
	v_mov_b32_e32 v25, 0
	v_mov_b32_e32 v26, 0
	v_mov_b32_e32 v27, 0
	v_mov_b32_e32 v28, 0
	v_mov_b32_e32 v29, 0
	v_mov_b32_e32 v30, 0
	v_mov_b32_e32 v31, 0
	v_mov_b32_e32 v48, 0
	v_mov_b32_e32 v49, 0
	v_mov_b32_e32 v50, 0
	v_mov_b32_e32 v51, 0
	v_mov_b32_e32 v52, 0
	v_mov_b32_e32 v53, 0
	v_mov_b32_e32 v54, 0
	v_mov_b32_e32 v55, 0
	v_mov_b32_e32 v56, 0
	v_mov_b32_e32 v57, 0
	v_mov_b32_e32 v58, 0
	v_mov_b32_e32 v59, 0
	v_mov_b32_e32 v60, 0
	v_mov_b32_e32 v61, 0
	v_mov_b32_e32 v62, 0
	v_mov_b32_e32 v63, 0
	v_mov_b32_e32 v0, 0
	v_mov_b32_e32 v1, 0
	v_mov_b32_e32 v2, 0
	v_mov_b32_e32 v3, 0
	v_mov_b32_e32 v4, 0
	v_mov_b32_e32 v5, 0
	v_mov_b32_e32 v6, 0
	v_mov_b32_e32 v7, 0
	v_mov_b32_e32 v8, 0
	v_mov_b32_e32 v9, 0
	v_mov_b32_e32 v10, 0
	v_mov_b32_e32 v11, 0
	v_mov_b32_e32 v12, 0
	v_mov_b32_e32 v13, 0
	v_mov_b32_e32 v14, 0
	v_mov_b32_e32 v15, 0
